# P7: workgroups 96..255 run their PLE-GEMM tail units before their in_ret units (same work, different order) so the groups' epilogue store bursts interleave
# speedup vs baseline: 1.1440x; 1.0040x over previous
.LBB0_996:
	s_or_b64 exec, exec, s[0:1]
	s_cmpk_lt_i32 s2, 0x660
	s_cselect_b64 s[0:1], -1, 0
	v_mov_b32_e32 v8, v198
	s_waitcnt lgkmcnt(0)
	s_barrier
	s_mov_b32 s72, 0
	s_cmp_lt_u32 s2, 96
	s_cbranch_scc1 .Lp7_main
	s_mov_b32 s72, 1
	s_mov_b64 s[70:71], s[68:69]
	s_branch .LBB0_1148
.Lp7_main:
	s_and_b64 vcc, exec, s[0:1]
	v_readfirstlane_b32 s24, v8
	s_cbranch_vccz .LBB0_998
	v_readlane_b32 s6, v254, 33
	v_readlane_b32 s7, v254, 34
	s_movk_i32 s8, 0xcd
	s_and_b64 s[6:7], s[6:7], exec
	s_cselect_b32 s6, s8, 0xcc
	s_mul_i32 s6, s33, s6
	v_readlane_b32 s7, v254, 32
	s_add_i32 s6, s6, s7
	s_mul_hi_i32 s7, s6, 0x2aaaaaab
	s_lshr_b32 s8, s7, 31
	s_ashr_i32 s7, s7, 5
	s_add_i32 s7, s7, s8
	s_lshl_b32 s8, s7, 3
	s_sub_i32 s9, 0x44, s8
	s_min_u32 s9, s9, 8
	s_mulk_i32 s7, 0xc0
	s_sub_i32 s10, s6, s7
	v_cvt_f32_ubyte0_e32 v1, s9
	v_cvt_f32_i32_e32 v0, s10
	v_rcp_iflag_f32_e32 v2, v1
	s_ashr_i32 s6, s10, 30
	s_or_b32 s11, s6, 1
	v_mul_f32_e32 v2, v0, v2
	v_trunc_f32_e32 v2, v2
	v_fma_f32 v0, -v2, v1, v0
	v_cvt_i32_f32_e32 v2, v2
	v_cmp_ge_f32_e64 s[6:7], |v0|, v1
	s_and_b64 s[6:7], s[6:7], exec
	s_cselect_b32 s6, s11, 0
	v_readfirstlane_b32 s7, v2
	s_add_i32 s6, s7, s6
	s_sext_i32_i16 s38, s6
	s_mul_i32 s6, s6, s9
	s_sub_i32 s6, s10, s6
	s_sext_i32_i16 s6, s6
	s_add_i32 s40, s8, s6

.LBB0_1148:
	s_add_u32 s24, s94, 0x4b82800
	s_addc_u32 s25, s95, 0
	s_cmp_eq_u32 s72, 2
	s_cbranch_scc1 .LBB0_1177
	s_mov_b64 s[0:1], -1
	s_and_b64 vcc, exec, s[46:47]
	s_cbranch_vccz .LBB0_1168
	v_readlane_b32 s0, v254, 55
	v_mov_b32_e32 v8, v198
	v_readlane_b32 s1, v254, 56
	s_and_b64 vcc, exec, s[0:1]
	v_readfirstlane_b32 s33, v8
	s_cbranch_vccnz .LBB0_1167
	v_lshlrev_b32_e32 v0, 4, v8
	v_add_u32_e32 v1, 0x2000, v0
	v_ashrrev_i32_e32 v2, 31, v1
	v_lshrrev_b32_e32 v2, 22, v2
	v_add_u32_e32 v2, v1, v2
	v_ashrrev_i32_e32 v2, 10, v2
	v_mul_i32_i24_e32 v3, 0x400, v2
	v_sub_u32_e32 v1, v1, v3
	v_lshrrev_b32_e32 v3, 4, v1
	v_bitop3_b32 v1, v3, v1, 32 bitop3:0x6c
	s_ashr_i32 s6, s33, 6
	v_ashrrev_i32_e32 v3, 31, v1
	v_readlane_b32 s8, v254, 33
	s_ashr_i32 s1, s33, 8
	s_lshl_b32 s49, s6, 10
	v_lshrrev_b32_e32 v3, 26, v3
	v_readlane_b32 s9, v254, 34
	v_add_u32_e32 v3, v1, v3
	s_and_b64 s[8:9], s[8:9], exec
	v_readlane_b32 s0, v254, 49
	v_readlane_b32 s7, v254, 50
	v_lshrrev_b32_e32 v4, 6, v3
	v_lshlrev_b32_e32 v5, 3, v2
	v_and_b32_e32 v3, 0xc0, v3
	s_cselect_b32 s0, s7, s0
	v_readlane_b32 s7, v254, 32
	v_and_b32_e32 v5, 0x7ffff0, v5
	v_lshlrev_b32_e32 v2, 5, v2
	v_sub_u32_e32 v1, v1, v3
	v_mov_b32_e32 v3, 1
	s_add_i32 s0, s0, s7
	v_add_u32_e32 v4, v4, v5
	v_and_b32_e32 v2, 32, v2
	v_ashrrev_i16_sdwa v1, v3, sext(v1) dst_sel:DWORD dst_unused:UNUSED_PAD src0_sel:DWORD src1_sel:BYTE_0
	s_ashr_i32 s7, s0, 31
	v_lshl_or_b32 v2, v4, 8, v2
	v_bfe_i32 v1, v1, 0, 16
	s_lshr_b32 s7, s7, 27
	v_add_lshl_u32 v128, v2, v1, 1
	v_bfe_i32 v1, v8, 27, 1
	s_add_i32 s7, s0, s7
	v_lshrrev_b32_e32 v1, 22, v1
	s_ashr_i32 s8, s7, 5
	s_and_b32 s7, s7, 0xffe0
	v_add_u32_e32 v1, v0, v1
	s_sub_i32 s7, s0, s7
	v_and_b32_e32 v1, 0xfffffc00, v1
	s_bfe_i32 s0, s7, 0x80000
	v_sub_u32_e32 v0, v0, v1
	v_ashrrev_i32_e32 v2, 31, v8
	s_bfe_u32 s0, s0, 0x3000c
	v_lshrrev_b32_e32 v1, 4, v0
	v_lshrrev_b32_e32 v2, 26, v2
	s_add_i32 s9, s7, s0
	v_bitop3_b32 v1, v1, v0, 32 bitop3:0x6c
	v_ashrrev_i32_e32 v0, 31, v0
	v_add_u32_e32 v2, v8, v2
	s_bfe_i32 s0, s9, 0x80000
	s_and_b32 s9, s9, 0xf8
	v_lshrrev_b32_e32 v0, 26, v0
	v_ashrrev_i32_e32 v2, 6, v2
	s_sub_i32 s7, s7, s9
	v_add_u32_e32 v0, v1, v0
	v_lshlrev_b32_e32 v4, 3, v2
	s_lshl_b32 s8, s8, 3
	s_sext_i32_i16 s0, s0
	s_sext_i32_i8 s7, s7
	v_ashrrev_i32_e32 v0, 6, v0
	v_and_b32_e32 v4, 0x7ffff0, v4
	s_lshr_b32 s0, s0, 3
	s_add_i32 s18, s8, s7
	v_add_u32_e32 v4, v0, v4
	v_mul_i32_i24_e32 v0, 64, v0
	s_ashr_i32 s19, s18, 31
	s_bfe_i64 s[10:11], s[0:1], 0x100000
	v_lshlrev_b32_e32 v2, 5, v2
	v_sub_u32_e32 v0, v1, v0
	s_lshl_b64 s[8:9], s[18:19], 17
	s_lshl_b64 s[10:11], s[10:11], 17
	v_readlane_b32 s14, v254, 23
	v_and_b32_e32 v2, 32, v2
	v_ashrrev_i16_sdwa v0, v3, sext(v0) dst_sel:DWORD dst_unused:UNUSED_PAD src0_sel:DWORD src1_sel:BYTE_0
	v_readlane_b32 s15, v254, 24
	s_add_u32 s20, s14, s10
	v_lshl_or_b32 v2, v4, 8, v2
	v_bfe_i32 v0, v0, 0, 16
	s_addc_u32 s21, s15, s11
	s_add_i32 s19, s49, 0
	v_add_lshl_u32 v130, v2, v0, 1
	s_add_i32 m0, s19, 0x10000
	v_mov_b32_e32 v131, 0
	global_load_lds_dwordx4 v130, s[20:21]
	s_add_i32 m0, s19, 0x12000
	s_add_u32 s22, s24, s8
	global_load_lds_dwordx4 v128, s[20:21]
	s_addc_u32 s23, s25, s9
	s_mov_b32 m0, s19
	s_add_i32 s50, s19, 0x2000
	global_load_lds_dwordx4 v130, s[22:23]
	s_mov_b32 m0, s50
	s_add_u32 s8, s20, 0x10000
	global_load_lds_dwordx4 v128, s[22:23]
	s_addc_u32 s9, s21, 0
	s_add_i32 m0, s19, 0x14000
	v_mov_b32_e32 v129, v131
	global_load_lds_dwordx4 v130, s[8:9]
	s_add_i32 m0, s19, 0x16000
	s_mov_b32 s53, 0
	global_load_lds_dwordx4 v128, s[8:9]
	s_add_u32 s8, s22, 0x10000
	s_addc_u32 s9, s23, 0
	s_add_i32 s51, s19, 0x4000
	s_mov_b32 m0, s51
	s_add_i32 s52, s19, 0x6000
	global_load_lds_dwordx4 v130, s[8:9]
	s_mov_b32 m0, s52
	v_lshl_add_u64 v[6:7], s[20:21], 0, v[130:131]
	global_load_lds_dwordx4 v128, s[8:9]
	v_lshl_add_u64 v[4:5], s[20:21], 0, v[128:129]
	v_lshl_add_u64 v[2:3], s[22:23], 0, v[130:131]
	s_cmp_lg_u32 s1, 1
	v_lshl_add_u64 v[0:1], s[22:23], 0, v[128:129]
	s_cbranch_scc1 .LBB0_1152
	s_barrier

.LBB0_1177:
	s_cmp_eq_u32 s72, 1
	s_cbranch_scc0 .Lp7_ple_done
	v_readlane_b32 s33, v254, 44
	s_mov_b32 s72, 2
	s_mov_b64 s[68:69], s[70:71]
	s_cmpk_lt_i32 s2, 0x660
	s_cselect_b64 s[0:1], -1, 0
	v_mov_b32_e32 v8, v198
	s_nop 3
	s_branch .Lp7_main
